# attn192 k-tile loop: workgroup barrier moved from before the tile's 10 global loads to just before the first LDS write
# speedup vs baseline: 1.0022x; 1.0022x over previous
; #define MFMA(a, b, c) __builtin_amdgcn_mfma_f32_32x32x16_bf16((a), (b), (c), 0, 0, 0)
; template <int DQ, bool MASK>
; DI void attn_phase(const Params& p, unsigned char* smem, float cexp) {
;     ...
;     for (int kt = 0; kt < ntile_block; ++kt) {
;       __syncthreads();
;       {
;         constexpr int CPR = DQ / 8;
; #pragma unroll
;         for (int i = 0; i < DQ / 32; ++i) {
;           int c = tid + 256 * i;
;           int row = c / CPR, cc = c % CPR;
;           uint4 v = *(const uint4*)(Kb + ((size_t)bh * 2048 + kt * 64 + row) * DQ + cc * 8);
;           *(uint4*)(Ks + row * KST + cc * 8) = v;
;         }
; #pragma unroll
;         for (int i = 0; i < 4; ++i) {
;           int c = tid + 256 * i;
;           int d = c >> 3, cc = c & 7;
;           uint4 v = *(const uint4*)(Vt + (((size_t)bh * 32 + kt) * 128 + d) * 64 + cc * 8);
;           uint2* dp = (uint2*)(Vs + d * VST + cc * 8);
;           dp[0] = make_uint2(v.x, v.y);
;           dp[1] = make_uint2(v.z, v.w);
;         }
;       }
;       __syncthreads();
;       if (kt < my_nt) {
;         f32x16 sa[2];
; #pragma unroll
;         for (int u = 0; u < 2; ++u) {
; #pragma unroll
;           for (int i = 0; i < 16; ++i) sa[u][i] = 0.f;
; #pragma unroll
;           for (int s = 0; s < DQ / 16; ++s) {
;             bf16x8 a = *(const bf16x8*)(Ks + (32 * u + r) * KST + 16 * s + 8 * g);
;             sa[u] = MFMA(a, qf[s], sa[u]);
;           }
;         }
;         if (MASK) {
;           u64 mw = mask[tok * 32 + kt] >> (4 * g);
;           const u32 mlo = (u32)mw, mhi = (u32)(mw >> 32);
; #pragma unroll
;           for (int i = 0; i < 16; ++i) {
;             const u32 bit = 1u << ((i & 3) + 8 * (i >> 2));
;             if (!(mlo & bit)) sa[0][i] = -INFINITY;
;             if (!(mhi & bit)) sa[1][i] = -INFINITY;
;           }
;         }
;         float mx = -INFINITY;
; #pragma unroll
;         for (int u = 0; u < 2; ++u)
; #pragma unroll
;           for (int i = 0; i < 16; ++i) mx = fmaxf(mx, sa[u][i]);
;         mx = fmaxf(mx, __shfl_xor(mx, 32));
.LBB0_422:
	v_lshl_add_u64 v[2:3], s[22:23], 0, v[206:207]
	v_lshl_add_u64 v[6:7], s[22:23], 0, v[208:209]
	v_lshl_add_u64 v[10:11], s[22:23], 0, v[210:211]
	v_lshl_add_u64 v[14:15], s[22:23], 0, v[212:213]
	global_load_dwordx4 v[2:5], v[2:3], off
	s_nop 0
	global_load_dwordx4 v[6:9], v[6:7], off
	s_nop 0
	global_load_dwordx4 v[10:13], v[10:11], off
	s_nop 0
	global_load_dwordx4 v[80:83], v[14:15], off
	v_lshl_add_u64 v[14:15], s[22:23], 0, v[214:215]
	v_lshl_add_u64 v[88:89], s[22:23], 0, v[216:217]
	global_load_dwordx4 v[84:87], v[14:15], off
	s_nop 0
	global_load_dwordx4 v[88:91], v[88:89], off
	v_lshl_add_u64 v[14:15], s[22:23], 0, v[204:205]
	v_add_co_u32_e32 v14, vcc, s62, v14
	v_lshl_add_u64 v[92:93], s[22:23], 0, v[202:203]
	s_nop 0
	v_addc_co_u32_e32 v15, vcc, 0, v15, vcc
	v_add_co_u32_e32 v96, vcc, s62, v92
	v_lshl_add_u64 v[100:101], s[22:23], 0, v[198:199]
	s_nop 0
	v_addc_co_u32_e32 v97, vcc, 0, v93, vcc
	global_load_dwordx4 v[92:95], v[14:15], off
	s_nop 0
	global_load_dwordx4 v[96:99], v[96:97], off
	v_lshl_add_u64 v[14:15], s[22:23], 0, v[200:201]
	v_add_co_u32_e32 v14, vcc, s62, v14
	s_nop 1
	v_addc_co_u32_e32 v15, vcc, 0, v15, vcc
	v_add_co_u32_e32 v104, vcc, 0xe000000, v100
	s_nop 1
	v_addc_co_u32_e32 v105, vcc, 0, v101, vcc
	global_load_dwordx4 v[100:103], v[14:15], off
	s_nop 0
	global_load_dwordx4 v[104:107], v[104:105], off
	v_cmp_lt_i32_e32 vcc, s54, v197
	s_barrier
	s_waitcnt vmcnt(9)
	ds_write_b128 v229, v[2:5]
	s_waitcnt vmcnt(8)
	ds_write_b128 v230, v[6:9]
	s_waitcnt vmcnt(7)
	ds_write_b128 v231, v[10:13]
	s_waitcnt vmcnt(6)
	ds_write_b128 v232, v[80:83]
	s_waitcnt vmcnt(5)
	ds_write_b128 v233, v[84:87]
	s_waitcnt vmcnt(4)
	ds_write_b128 v234, v[88:91]
	s_waitcnt vmcnt(3)
	ds_write2_b64 v235, v[92:93], v[94:95] offset1:1
	s_waitcnt vmcnt(2)
	ds_write2_b64 v236, v[96:97], v[98:99] offset1:1
	s_waitcnt vmcnt(1)
	ds_write2_b64 v237, v[100:101], v[102:103] offset1:1
	s_waitcnt vmcnt(0)
	ds_write2_b64 v238, v[104:105], v[106:107] offset1:1
	s_waitcnt lgkmcnt(0)
	s_barrier
	s_and_saveexec_b64 s[12:13], vcc
	s_cbranch_execz .LBB0_421
	ds_read_b128 v[2:5], v239
	ds_read_b128 v[6:9], v239 offset:12800
	ds_read_b128 v[244:247], v239 offset:32
	ds_read_b128 v[248:251], v239 offset:12832
	s_waitcnt lgkmcnt(3)
	v_mfma_f32_32x32x16_bf16 v[96:111], v[2:5], v[112:115], 0
	ds_read_b128 v[2:5], v239 offset:64
	s_waitcnt lgkmcnt(3)
	v_mfma_f32_32x32x16_bf16 v[80:95], v[6:9], v[112:115], 0
	ds_read_b128 v[6:9], v239 offset:12864
	s_waitcnt lgkmcnt(3)
	v_mfma_f32_32x32x16_bf16 v[96:111], v[244:247], v[116:119], v[96:111]
	ds_read_b128 v[244:247], v239 offset:96
	s_waitcnt lgkmcnt(3)
	v_mfma_f32_32x32x16_bf16 v[80:95], v[248:251], v[116:119], v[80:95]
	ds_read_b128 v[248:251], v239 offset:12896
	s_waitcnt lgkmcnt(3)
	v_mfma_f32_32x32x16_bf16 v[96:111], v[2:5], v[120:123], v[96:111]
	ds_read_b128 v[2:5], v239 offset:128
	s_waitcnt lgkmcnt(3)
	v_mfma_f32_32x32x16_bf16 v[80:95], v[6:9], v[120:123], v[80:95]
	ds_read_b128 v[6:9], v239 offset:12928
	s_waitcnt lgkmcnt(3)
	v_mfma_f32_32x32x16_bf16 v[96:111], v[244:247], v[124:127], v[96:111]
	ds_read_b128 v[244:247], v239 offset:160
	s_waitcnt lgkmcnt(3)
	v_mfma_f32_32x32x16_bf16 v[80:95], v[248:251], v[124:127], v[80:95]
	ds_read_b128 v[248:251], v239 offset:12960
	s_waitcnt lgkmcnt(3)
	v_mfma_f32_32x32x16_bf16 v[96:111], v[2:5], v[128:131], v[96:111]
	ds_read_b128 v[2:5], v239 offset:192
	s_waitcnt lgkmcnt(3)
	v_mfma_f32_32x32x16_bf16 v[80:95], v[6:9], v[128:131], v[80:95]
	ds_read_b128 v[6:9], v239 offset:12992
	s_waitcnt lgkmcnt(3)
	v_mfma_f32_32x32x16_bf16 v[96:111], v[244:247], v[132:135], v[96:111]
	ds_read_b128 v[244:247], v239 offset:224
	s_waitcnt lgkmcnt(3)
	v_mfma_f32_32x32x16_bf16 v[80:95], v[248:251], v[132:135], v[80:95]
	ds_read_b128 v[248:251], v239 offset:13024
	s_waitcnt lgkmcnt(3)
	v_mfma_f32_32x32x16_bf16 v[96:111], v[2:5], v[136:139], v[96:111]
	ds_read_b128 v[2:5], v239 offset:256
	s_waitcnt lgkmcnt(3)
	v_mfma_f32_32x32x16_bf16 v[80:95], v[6:9], v[136:139], v[80:95]
	ds_read_b128 v[6:9], v239 offset:13056
	s_waitcnt lgkmcnt(3)
	v_mfma_f32_32x32x16_bf16 v[96:111], v[244:247], v[140:143], v[96:111]
	ds_read_b128 v[244:247], v239 offset:288
	s_waitcnt lgkmcnt(3)
	v_mfma_f32_32x32x16_bf16 v[80:95], v[248:251], v[140:143], v[80:95]
	ds_read_b128 v[248:251], v239 offset:13088
	s_waitcnt lgkmcnt(3)
	v_mfma_f32_32x32x16_bf16 v[96:111], v[2:5], v[144:147], v[96:111]
	ds_read_b128 v[2:5], v239 offset:320
	s_waitcnt lgkmcnt(3)
	v_mfma_f32_32x32x16_bf16 v[80:95], v[6:9], v[144:147], v[80:95]
	ds_read_b128 v[6:9], v239 offset:13120
	s_waitcnt lgkmcnt(3)
	v_mfma_f32_32x32x16_bf16 v[96:111], v[244:247], v[148:151], v[96:111]
	ds_read_b128 v[244:247], v239 offset:352
	s_waitcnt lgkmcnt(3)
	v_mfma_f32_32x32x16_bf16 v[80:95], v[248:251], v[148:151], v[80:95]
	ds_read_b128 v[248:251], v239 offset:13152
	s_waitcnt lgkmcnt(3)
	v_mfma_f32_32x32x16_bf16 v[96:111], v[2:5], v[152:155], v[96:111]
	s_waitcnt lgkmcnt(2)
	v_mfma_f32_32x32x16_bf16 v[80:95], v[6:9], v[152:155], v[80:95]
	s_waitcnt lgkmcnt(1)
	v_mfma_f32_32x32x16_bf16 v[96:111], v[244:247], v[156:159], v[96:111]
	s_waitcnt lgkmcnt(0)
	v_mfma_f32_32x32x16_bf16 v[80:95], v[248:251], v[156:159], v[80:95]
	s_nop 7
	s_nop 3
	v_max3_f32 v1, v96, s64, v97
	v_max3_f32 v1, v1, v98, v99
	v_max3_f32 v1, v1, v100, v101
	v_max3_f32 v1, v1, v102, v103
	v_max3_f32 v1, v1, v104, v105
	v_max3_f32 v1, v1, v106, v107
	v_max3_f32 v1, v1, v108, v109
	v_max3_f32 v1, v1, v110, v111
	s_nop 1
	v_max3_f32 v1, v1, v80, v81
	v_max3_f32 v1, v1, v82, v83
	v_max3_f32 v1, v1, v84, v85
	v_max3_f32 v1, v1, v86, v87
	v_max3_f32 v1, v1, v88, v89
	v_max3_f32 v1, v1, v90, v91
	v_max3_f32 v1, v1, v92, v93
	v_max3_f32 v1, v1, v94, v95
	v_mov_b32_e32 v2, v1
	s_nop 1
	v_permlane32_swap_b32_e32 v1, v2
	s_waitcnt lgkmcnt(0)
; #define MFMA(a, b, c) __builtin_amdgcn_mfma_f32_32x32x16_bf16((a), (b), (c), 0, 0, 0)
; template <int DQ, bool MASK>
; DI void attn_phase(const Params& p, unsigned char* smem, float cexp) {
;     ...
;         float mnew = fmaxf(m, mx);
;         float muse = (mnew == -INFINITY) ? 0.f : mnew;
;         float alpha = __builtin_amdgcn_exp2f((m - muse) * cexp);
;         m = mnew;
;         float ps = 0.f;
; #pragma unroll
;         for (int u = 0; u < 2; ++u)
; #pragma unroll
;           for (int i = 0; i < 16; ++i) {
;             float pv = __builtin_amdgcn_exp2f((sa[u][i] - muse) * cexp);
;             ps += pv;
;             sa[u][i] = pv;
;           }
;         l = l * alpha + ps;
; #pragma unroll
;         for (int j = 0; j < 4; ++j)
; #pragma unroll
;           for (int i = 0; i < 16; ++i) o[j][i] *= alpha;
; #pragma unroll
;         for (int u = 0; u < 2; ++u)
; #pragma unroll
;           for (int s2 = 0; s2 < 2; ++s2) {
;             uint4 pp;
;             pp.x = pack2(sa[u][8 * s2 + 0], sa[u][8 * s2 + 1]);
;             pp.y = pack2(sa[u][8 * s2 + 2], sa[u][8 * s2 + 3]);
;             pp.z = pack2(sa[u][8 * s2 + 4], sa[u][8 * s2 + 5]);
;             pp.w = pack2(sa[u][8 * s2 + 6], sa[u][8 * s2 + 7]);
;             bf16x8 pf = __builtin_bit_cast(bf16x8, pp);
; #pragma unroll
;             for (int dt = 0; dt < 4; ++dt) {
;               const bf16* vp = Vs + (32 * dt + r) * VST + 32 * u + 16 * s2 + 4 * g;
;               s16x4 lo = *(const s16x4*)vp;
;               s16x4 hi = *(const s16x4*)(vp + 8);
;               bf16x8 vf = __builtin_shufflevector(lo, hi, 0, 1, 2, 3, 4, 5, 6, 7);
;               o[dt] = MFMA(vf, pf, o[dt]);
;             }
;           }
	v_max3_f32 v1, v242, v1, v2
	v_cmp_neq_f32_e32 vcc, s64, v1
	s_nop 1
	v_cndmask_b32_e32 v3, 0, v1, vcc
	v_sub_f32_e32 v5, v100, v3
	v_mul_f32_e32 v5, 0x3dd53b94, v5
	v_exp_f32_e32 v12, v5
	v_sub_f32_e32 v5, v101, v3
	v_mul_f32_e32 v5, 0x3dd53b94, v5
	v_sub_f32_e32 v4, v96, v3
	v_exp_f32_e32 v13, v5
	v_sub_f32_e32 v5, v102, v3
	v_mul_f32_e32 v4, 0x3dd53b94, v4
	v_mul_f32_e32 v5, 0x3dd53b94, v5
	v_exp_f32_e32 v8, v4
	v_sub_f32_e32 v4, v97, v3
	v_exp_f32_e32 v14, v5
	v_sub_f32_e32 v5, v103, v3
	v_mul_f32_e32 v4, 0x3dd53b94, v4
	v_mul_f32_e32 v5, 0x3dd53b94, v5
	v_exp_f32_e32 v9, v4
	v_sub_f32_e32 v4, v98, v3
	v_exp_f32_e32 v15, v5
	v_sub_f32_e32 v5, v104, v3
	v_mul_f32_e32 v4, 0x3dd53b94, v4
	v_mul_f32_e32 v5, 0x3dd53b94, v5
	v_exp_f32_e32 v10, v4
	v_sub_f32_e32 v4, v99, v3
	v_exp_f32_e32 v96, v5
	v_sub_f32_e32 v5, v105, v3
	v_mul_f32_e32 v4, 0x3dd53b94, v4
	v_mul_f32_e32 v5, 0x3dd53b94, v5
	v_exp_f32_e32 v11, v4
	v_exp_f32_e32 v97, v5
	v_sub_f32_e32 v5, v106, v3
	v_add_f32_e32 v4, 0, v8
	v_mul_f32_e32 v5, 0x3dd53b94, v5
	v_add_f32_e32 v4, v9, v4
	v_exp_f32_e32 v98, v5
	v_sub_f32_e32 v5, v107, v3
	v_add_f32_e32 v4, v10, v4
	v_mul_f32_e32 v5, 0x3dd53b94, v5
	v_add_f32_e32 v4, v11, v4
	v_exp_f32_e32 v99, v5
	v_sub_f32_e32 v5, v108, v3
	v_add_f32_e32 v4, v12, v4
	v_mul_f32_e32 v5, 0x3dd53b94, v5
	v_add_f32_e32 v4, v13, v4
	v_exp_f32_e32 v100, v5
	v_sub_f32_e32 v5, v109, v3
	v_add_f32_e32 v4, v14, v4
	v_mul_f32_e32 v5, 0x3dd53b94, v5
	v_add_f32_e32 v4, v15, v4
	v_exp_f32_e32 v101, v5
	v_sub_f32_e32 v5, v110, v3
	v_add_f32_e32 v4, v96, v4
	v_mul_f32_e32 v5, 0x3dd53b94, v5
	v_add_f32_e32 v4, v97, v4
	v_exp_f32_e32 v102, v5
	v_sub_f32_e32 v5, v111, v3
	v_add_f32_e32 v4, v98, v4
	v_mul_f32_e32 v5, 0x3dd53b94, v5
	v_add_f32_e32 v4, v99, v4
	v_exp_f32_e32 v103, v5
	v_add_f32_e32 v4, v100, v4
	v_add_f32_e32 v4, v101, v4
	v_add_f32_e32 v4, v102, v4
	v_add_f32_e32 v104, v103, v4
	v_sub_f32_e32 v4, v80, v3
	v_mul_f32_e32 v4, 0x3dd53b94, v4
	v_exp_f32_e32 v80, v4
	v_sub_f32_e32 v4, v81, v3
	v_mul_f32_e32 v4, 0x3dd53b94, v4
	v_add_u32_e32 v105, 0x6000, v240
	v_exp_f32_e32 v81, v4
	ds_read2_b64 v[4:7], v105 offset0:128 offset1:130
	v_sub_f32_e32 v2, v242, v3
	v_mul_f32_e32 v2, 0x3dd53b94, v2
	v_exp_f32_e32 v2, v2
	v_add_u32_e32 v106, 0x7000, v240
	v_cvt_pk_bf16_f32 v8, v8, v9
	v_cvt_pk_bf16_f32 v9, v10, v11
	v_cvt_pk_bf16_f32 v10, v12, v13
	v_cvt_pk_bf16_f32 v11, v14, v15
	ds_read2_b64 v[12:15], v106 offset0:160 offset1:162
	v_pk_mul_f32 v[78:79], v[78:79], v[2:3] op_sel_hi:[1,0]
	v_pk_mul_f32 v[76:77], v[76:77], v[2:3] op_sel_hi:[1,0]
	v_pk_mul_f32 v[74:75], v[74:75], v[2:3] op_sel_hi:[1,0]
	v_pk_mul_f32 v[72:73], v[72:73], v[2:3] op_sel_hi:[1,0]
	v_pk_mul_f32 v[70:71], v[70:71], v[2:3] op_sel_hi:[1,0]
	v_pk_mul_f32 v[68:69], v[68:69], v[2:3] op_sel_hi:[1,0]
	v_pk_mul_f32 v[66:67], v[66:67], v[2:3] op_sel_hi:[1,0]
	v_pk_mul_f32 v[64:65], v[64:65], v[2:3] op_sel_hi:[1,0]
	v_add_u32_e32 v107, 0x8000, v240
	v_pk_mul_f32 v[62:63], v[62:63], v[2:3] op_sel_hi:[1,0]
	s_waitcnt lgkmcnt(1)
	v_mfma_f32_32x32x16_bf16 v[64:79], v[4:7], v[8:11], v[64:79]
	ds_read2_b64 v[4:7], v107 offset0:192 offset1:194
	v_mul_f32_e64 v60, v60, v2
	v_mul_f32_e64 v61, v61, v2
	v_mul_f32_e64 v58, v58, v2
	v_mul_f32_e64 v59, v59, v2
	v_pk_mul_f32 v[56:57], v[56:57], v[2:3] op_sel_hi:[1,0]
	v_pk_mul_f32 v[54:55], v[54:55], v[2:3] op_sel_hi:[1,0]
	v_pk_mul_f32 v[52:53], v[52:53], v[2:3] op_sel_hi:[1,0]
	v_pk_mul_f32 v[50:51], v[50:51], v[2:3] op_sel_hi:[1,0]
	v_pk_mul_f32 v[48:49], v[48:49], v[2:3] op_sel_hi:[1,0]
	v_add_u32_e32 v108, 0x9000, v240
	v_pk_mul_f32 v[46:47], v[46:47], v[2:3] op_sel_hi:[1,0]
	s_waitcnt lgkmcnt(1)
	v_mfma_f32_32x32x16_bf16 v[48:63], v[12:15], v[8:11], v[48:63]
	ds_read2_b64 v[12:15], v108 offset0:224 offset1:226
	v_mul_f32_e64 v44, v44, v2
	v_mul_f32_e64 v45, v45, v2
	v_mul_f32_e64 v42, v42, v2
	v_mul_f32_e64 v43, v43, v2
	v_pk_mul_f32 v[40:41], v[40:41], v[2:3] op_sel_hi:[1,0]
	v_pk_mul_f32 v[38:39], v[38:39], v[2:3] op_sel_hi:[1,0]
	v_pk_mul_f32 v[36:37], v[36:37], v[2:3] op_sel_hi:[1,0]
	v_pk_mul_f32 v[34:35], v[34:35], v[2:3] op_sel_hi:[1,0]
	v_pk_mul_f32 v[32:33], v[32:33], v[2:3] op_sel_hi:[1,0]
	v_pk_mul_f32 v[30:31], v[30:31], v[2:3] op_sel_hi:[1,0]
	v_pk_mul_f32 v[28:29], v[28:29], v[2:3] op_sel_hi:[1,0]
	s_waitcnt lgkmcnt(1)
; #define MFMA(a, b, c) __builtin_amdgcn_mfma_f32_32x32x16_bf16((a), (b), (c), 0, 0, 0)
; template <int DQ, bool MASK>
; DI void attn_phase(const Params& p, unsigned char* smem, float cexp) {
;     ...
;         float ps = 0.f;
; #pragma unroll
;         for (int u = 0; u < 2; ++u)
; #pragma unroll
;           for (int i = 0; i < 16; ++i) {
;             float pv = __builtin_amdgcn_exp2f((sa[u][i] - muse) * cexp);
;             ps += pv;
;             sa[u][i] = pv;
;           }
;         l = l * alpha + ps;
; #pragma unroll
;         for (int j = 0; j < 4; ++j)
; #pragma unroll
;           for (int i = 0; i < 16; ++i) o[j][i] *= alpha;
; #pragma unroll
;         for (int u = 0; u < 2; ++u)
; #pragma unroll
;           for (int s2 = 0; s2 < 2; ++s2) {
;             uint4 pp;
;             pp.x = pack2(sa[u][8 * s2 + 0], sa[u][8 * s2 + 1]);
;             pp.y = pack2(sa[u][8 * s2 + 2], sa[u][8 * s2 + 3]);
;             pp.z = pack2(sa[u][8 * s2 + 4], sa[u][8 * s2 + 5]);
;             pp.w = pack2(sa[u][8 * s2 + 6], sa[u][8 * s2 + 7]);
;             bf16x8 pf = __builtin_bit_cast(bf16x8, pp);
; #pragma unroll
;             for (int dt = 0; dt < 4; ++dt) {
;               const bf16* vp = Vs + (32 * dt + r) * VST + 32 * u + 16 * s2 + 4 * g;
;               s16x4 lo = *(const s16x4*)vp;
;               s16x4 hi = *(const s16x4*)(vp + 8);
;               bf16x8 vf = __builtin_shufflevector(lo, hi, 0, 1, 2, 3, 4, 5, 6, 7);
;               o[dt] = MFMA(vf, pf, o[dt]);
;             }
;           }
;       }
	v_mfma_f32_32x32x16_bf16 v[32:47], v[4:7], v[8:11], v[32:47]
	ds_read2_b64 v[4:7], v105 offset0:132 offset1:134
	v_mul_f32_e64 v26, v26, v2
	v_mul_f32_e64 v27, v27, v2
	v_mul_f32_e64 v24, v24, v2
	v_mul_f32_e64 v25, v25, v2
	v_pk_mul_f32 v[22:23], v[22:23], v[2:3] op_sel_hi:[1,0]
	v_pk_mul_f32 v[20:21], v[20:21], v[2:3] op_sel_hi:[1,0]
	v_pk_mul_f32 v[18:19], v[18:19], v[2:3] op_sel_hi:[1,0]
	v_pk_mul_f32 v[16:17], v[16:17], v[2:3] op_sel_hi:[1,0]
	v_sub_f32_e32 v89, v89, v3
	v_sub_f32_e32 v91, v91, v3
	s_waitcnt lgkmcnt(1)
	v_mfma_f32_32x32x16_bf16 v[16:31], v[12:15], v[8:11], v[16:31]
	v_sub_f32_e32 v8, v82, v3
	v_mul_f32_e32 v82, 0x3dd53b94, v8
	v_cvt_pk_bf16_f32 v8, v96, v97
	v_cvt_pk_bf16_f32 v9, v98, v99
	v_cvt_pk_bf16_f32 v10, v100, v101
	v_cvt_pk_bf16_f32 v11, v102, v103
	ds_read2_b64 v[12:15], v106 offset0:164 offset1:166
	v_exp_f32_e32 v82, v82
	s_waitcnt lgkmcnt(1)
	v_mfma_f32_32x32x16_bf16 v[64:79], v[4:7], v[8:11], v[64:79]
	v_sub_f32_e32 v4, v83, v3
	v_mul_f32_e32 v4, 0x3dd53b94, v4
	v_exp_f32_e32 v83, v4
	v_sub_f32_e32 v4, v84, v3
	v_mul_f32_e32 v84, 0x3dd53b94, v4
	ds_read2_b64 v[4:7], v107 offset0:196 offset1:198
	v_exp_f32_e32 v84, v84
	s_waitcnt lgkmcnt(1)
	v_mfma_f32_32x32x16_bf16 v[48:63], v[12:15], v[8:11], v[48:63]
	v_sub_f32_e32 v12, v85, v3
	v_mul_f32_e32 v12, 0x3dd53b94, v12
	v_exp_f32_e32 v85, v12
	v_sub_f32_e32 v12, v86, v3
	v_mul_f32_e32 v86, 0x3dd53b94, v12
	ds_read2_b64 v[12:15], v108 offset0:228 offset1:230
	v_exp_f32_e32 v86, v86
	s_waitcnt lgkmcnt(1)
	v_mfma_f32_32x32x16_bf16 v[32:47], v[4:7], v[8:11], v[32:47]
	v_sub_f32_e32 v4, v87, v3
	v_mul_f32_e32 v4, 0x3dd53b94, v4
	v_exp_f32_e32 v87, v4
	v_sub_f32_e32 v4, v88, v3
	v_mul_f32_e32 v88, 0x3dd53b94, v4
	ds_read2_b64 v[4:7], v105 offset0:136 offset1:138
	v_sub_f32_e32 v93, v93, v3
	s_waitcnt lgkmcnt(1)
	v_mfma_f32_32x32x16_bf16 v[16:31], v[12:15], v[8:11], v[16:31]
	v_cvt_pk_bf16_f32 v8, v80, v81
	v_cvt_pk_bf16_f32 v9, v82, v83
	v_cvt_pk_bf16_f32 v10, v84, v85
	v_cvt_pk_bf16_f32 v11, v86, v87
	ds_read2_b64 v[12:15], v106 offset0:168 offset1:170
	v_exp_f32_e32 v88, v88
	v_mov_b32_e32 v242, v1
	s_waitcnt lgkmcnt(1)
	v_mfma_f32_32x32x16_bf16 v[64:79], v[4:7], v[8:11], v[64:79]
	v_mul_f32_e32 v4, 0x3dd53b94, v89
	v_exp_f32_e32 v89, v4
	v_sub_f32_e32 v4, v90, v3
	v_mul_f32_e32 v4, 0x3dd53b94, v4
	v_exp_f32_e32 v90, v4
	ds_read2_b64 v[4:7], v107 offset0:200 offset1:202
	s_waitcnt lgkmcnt(1)
	v_mfma_f32_32x32x16_bf16 v[48:63], v[12:15], v[8:11], v[48:63]
	v_mul_f32_e32 v12, 0x3dd53b94, v91
	v_exp_f32_e32 v91, v12
	v_sub_f32_e32 v12, v92, v3
	v_mul_f32_e32 v12, 0x3dd53b94, v12
	v_exp_f32_e32 v92, v12
	ds_read2_b64 v[12:15], v108 offset0:232 offset1:234
	s_waitcnt lgkmcnt(1)
	v_mfma_f32_32x32x16_bf16 v[32:47], v[4:7], v[8:11], v[32:47]
	v_mul_f32_e32 v4, 0x3dd53b94, v93
	v_exp_f32_e32 v93, v4
	v_sub_f32_e32 v4, v94, v3
	v_mul_f32_e32 v4, 0x3dd53b94, v4
	v_exp_f32_e32 v94, v4
	ds_read2_b64 v[4:7], v105 offset0:140 offset1:142
	v_sub_f32_e32 v3, v95, v3
	v_mul_f32_e32 v3, 0x3dd53b94, v3
	v_exp_f32_e32 v3, v3
	s_waitcnt lgkmcnt(1)
	v_mfma_f32_32x32x16_bf16 v[16:31], v[12:15], v[8:11], v[16:31]
	ds_read2_b64 v[12:15], v106 offset0:172 offset1:174
	v_cvt_pk_bf16_f32 v8, v88, v89
	v_cvt_pk_bf16_f32 v9, v90, v91
	v_cvt_pk_bf16_f32 v10, v92, v93
	v_cvt_pk_bf16_f32 v11, v94, v3
	s_waitcnt lgkmcnt(1)
	s_nop 0
	v_mfma_f32_32x32x16_bf16 v[64:79], v[4:7], v[8:11], v[64:79]
	v_add_f32_e32 v4, v80, v104
	v_add_f32_e32 v4, v81, v4
	v_add_f32_e32 v4, v82, v4
	v_add_f32_e32 v4, v83, v4
	v_add_f32_e32 v4, v84, v4
	v_add_f32_e32 v80, v85, v4
	ds_read2_b64 v[4:7], v107 offset0:204 offset1:206
	s_waitcnt lgkmcnt(1)
	v_mfma_f32_32x32x16_bf16 v[48:63], v[12:15], v[8:11], v[48:63]
	v_add_f32_e32 v12, v86, v80
	v_add_f32_e32 v12, v87, v12
	v_add_f32_e32 v12, v88, v12
	v_add_f32_e32 v12, v89, v12
	v_add_f32_e32 v12, v90, v12
	v_add_f32_e32 v80, v91, v12
	ds_read2_b64 v[12:15], v108 offset0:236 offset1:238
	s_waitcnt lgkmcnt(1)
	v_mfma_f32_32x32x16_bf16 v[32:47], v[4:7], v[8:11], v[32:47]
	v_add_f32_e32 v4, v92, v80
	v_add_f32_e32 v4, v93, v4
	v_add_f32_e32 v4, v94, v4
	v_add_f32_e32 v3, v3, v4
	v_fmac_f32_e32 v3, v241, v2
	v_mov_b32_e32 v241, v3
	s_waitcnt lgkmcnt(0)
	v_mfma_f32_32x32x16_bf16 v[16:31], v[12:15], v[8:11], v[16:31]
	s_branch .LBB0_421
